# lever 4: one static s_setprio 1 for the attention compute waves (streaming waves stay at 0), reset at unit end
# baseline (speedup 1.0000x reference)
.LBB0_214:
	s_setprio 1
	s_lshl_b32 s40, s56, 3
	s_ashr_i32 s41, s40, 31
	v_lshl_add_u64 v[182:183], s[40:41], 1, v[192:193]
	s_lshl_b32 s40, s56, 4
	v_and_or_b32 v0, s40, 48, v198
	s_ashr_i32 s40, s42, 3
	s_andn2_b32 s40, s40, 31
	v_lshlrev_b32_e32 v0, 8, v0
	s_ashr_i32 s41, s40, 31
	s_lshl_b32 s43, s56, 10
	s_nop 0
	v_lshl_add_u64 v[2:3], s[6:7], 0, v[0:1]
	s_cmp_lg_u32 0, -1
	v_lshl_add_u64 v[2:3], s[40:41], 1, v[2:3]
	s_cselect_b32 s40, 0, 0
	v_mov_b32_e32 v191, v1
	s_add_i32 s60, s43, s40
	v_cndmask_b32_e64 v0, 0, 1, s[36:37]
	v_lshl_add_u64 v[184:185], v[2:3], 0, v[190:191]
	v_cmp_ne_u32_e64 s[40:41], 1, v0
	s_andn2_b64 vcc, exec, s[36:37]
	s_add_i32 s61, s60, 0x6000
	s_cbranch_vccnz .LBB0_216
	s_mov_b32 s36, m0
	s_mov_b32 m0, s60
	s_nop 0
	global_load_lds_dwordx4 v[182:183], off
	s_mov_b32 m0, s36
	s_cmp_lg_u32 0, -1
	s_mov_b32 s36, m0
	s_mov_b32 m0, s61
	s_nop 0
	global_load_lds_dwordx4 v[184:185], off
	s_mov_b32 m0, s36
	s_mov_b64 s[36:37], 0x4000
	v_lshl_add_u64 v[2:3], v[182:183], 0, s[36:37]
	s_cselect_b32 s36, 0, 0
	s_add_i32 s36, s36, s43
	s_addk_i32 s36, 0x2000
	s_mov_b32 s37, m0
	s_mov_b32 m0, s36
	s_nop 0
	global_load_lds_dwordx4 v[2:3], off
	s_mov_b32 m0, s37

.LBB0_241:
	v_add_f32_e32 v51, v82, v83
	v_add_f32_e32 v51, v84, v51
	v_add_f32_e32 v51, v85, v51
	v_add_f32_e32 v51, v86, v51
	v_add_f32_e32 v51, v87, v51
	v_add_f32_e32 v51, v88, v51
	v_add_f32_e32 v51, v89, v51
	v_add_f32_e32 v51, v90, v51
	v_add_f32_e32 v51, v91, v51
	v_add_f32_e32 v51, v92, v51
	v_add_f32_e32 v51, v93, v51
	v_add_f32_e32 v51, v94, v51
	v_add_f32_e32 v51, v95, v51
	v_add_f32_e32 v51, v96, v51
	v_add_f32_e32 v51, v97, v51
	v_add_f32_e32 v51, v34, v51
	v_add_f32_e32 v51, v35, v51
	v_add_f32_e32 v51, v36, v51
	v_add_f32_e32 v51, v37, v51
	v_add_f32_e32 v51, v38, v51
	v_add_f32_e32 v51, v39, v51
	v_add_f32_e32 v51, v40, v51
	v_add_f32_e32 v51, v41, v51
	v_add_f32_e32 v51, v42, v51
	v_add_f32_e32 v51, v43, v51
	v_add_f32_e32 v51, v44, v51
	v_add_f32_e32 v51, v45, v51
	v_add_f32_e32 v51, v46, v51
	v_add_f32_e32 v51, v47, v51
	s_cmp_lg_u32 0, -1
	v_add_f32_e32 v51, v48, v51
	s_cselect_b32 s2, 0, 0
	v_add_f32_e32 v51, v49, v51
	s_addk_i32 s2, 0x6000
	v_add_f32_e32 v51, v114, v51
	v_cvt_pk_bf16_f32 v34, v34, v35
	v_add3_u32 v60, v204, s2, v202
	v_cvt_pk_bf16_f32 v52, v82, v83
	v_cvt_pk_bf16_f32 v53, v84, v85
	v_cvt_pk_bf16_f32 v54, v86, v87
	v_cvt_pk_bf16_f32 v55, v88, v89
	v_cvt_pk_bf16_f32 v56, v90, v91
	v_cvt_pk_bf16_f32 v57, v92, v93
	v_cvt_pk_bf16_f32 v58, v94, v95
	v_cvt_pk_bf16_f32 v59, v96, v97
	v_cvt_pk_bf16_f32 v35, v36, v37
	v_cvt_pk_bf16_f32 v36, v38, v39
	v_cvt_pk_bf16_f32 v37, v40, v41
	v_cvt_pk_bf16_f32 v38, v42, v43
	v_cvt_pk_bf16_f32 v39, v44, v45
	v_cvt_pk_bf16_f32 v40, v46, v47
	v_cvt_pk_bf16_f32 v41, v48, v49
	v_add3_u32 v68, v60, v203, s44
	ds_read_b64_tr_b16 v[42:43],v68 offset:0
	ds_read_b64_tr_b16 v[44:45],v68 offset:512
	ds_read_b64_tr_b16 v[46:47],v68 offset:1024
	ds_read_b64_tr_b16 v[48:49],v68 offset:1536
	ds_read_b64_tr_b16 v[60:61],v68 offset:2048
	ds_read_b64_tr_b16 v[62:63],v68 offset:2560
	ds_read_b64_tr_b16 v[64:65],v68 offset:3072
	ds_read_b64_tr_b16 v[66:67],v68 offset:3584
	s_waitcnt lgkmcnt(0)
	s_nop 0
	v_mfma_f32_32x32x16_bf16 v[18:33], v[52:55], v[42:45], v[18:33]
	ds_read_b64_tr_b16 v[42:43],v68 offset:4096
	ds_read_b64_tr_b16 v[44:45],v68 offset:4608
	v_mfma_f32_32x32x16_bf16 v[18:33], v[56:59], v[46:49], v[18:33]
	ds_read_b64_tr_b16 v[46:47],v68 offset:5120
	ds_read_b64_tr_b16 v[48:49],v68 offset:5632
	v_mfma_f32_32x32x16_bf16 v[18:33], v[34:37], v[60:63], v[18:33]
	ds_read_b64_tr_b16 v[60:61],v68 offset:6144
	ds_read_b64_tr_b16 v[62:63],v68 offset:6656
	v_mfma_f32_32x32x16_bf16 v[18:33], v[38:41], v[64:67], v[18:33]
	ds_read_b64_tr_b16 v[64:65],v68 offset:7168
	ds_read_b64_tr_b16 v[66:67],v68 offset:7680
	s_waitcnt lgkmcnt(0)
	v_mfma_f32_32x32x16_bf16 v[2:17], v[52:55], v[42:45], v[2:17]
	v_cmp_gt_u32_e32 vcc, 32, v199
	v_mfma_f32_32x32x16_bf16 v[2:17], v[56:59], v[46:49], v[2:17]
	v_mfma_f32_32x32x16_bf16 v[2:17], v[34:37], v[60:63], v[2:17]
	v_mov_b32_e32 v34, v51
	s_nop 1
	v_permlane32_swap_b32_e32 v51, v34
	v_mfma_f32_32x32x16_bf16 v[2:17], v[38:41], v[64:67], v[2:17]
	s_and_saveexec_b64 s[2:3], vcc
	v_add_f32_e32 v34, v51, v34
	ds_write_b32 v0, v34 offset:57472
	s_or_b64 exec, exec, s[2:3]
	s_waitcnt lgkmcnt(0)
	ds_read_b128 v[34:37], v50 offset:57472
	ds_read_b128 v[38:41], v50 offset:57504
	s_lshl_b64 s[2:3], s[34:35], 11
	s_lshl_b32 s35, s56, 12
	s_add_i32 s35, s35, 0
	s_waitcnt lgkmcnt(1)
	v_rcp_f32_e32 v0, v34
	v_rcp_f32_e32 v42, v35
	v_rcp_f32_e32 v43, v36
	v_rcp_f32_e32 v44, v37
	s_waitcnt lgkmcnt(0)
	v_rcp_f32_e32 v45, v38
	ds_read_b128 v[34:37], v50 offset:57536
	v_rcp_f32_e32 v46, v39
	v_rcp_f32_e32 v47, v40
	v_rcp_f32_e32 v48, v41
	ds_read_b128 v[38:41], v50 offset:57568
	v_lshlrev_b32_e32 v49, 9, v201
	v_lshlrev_b32_e32 v50, 1, v191
	v_mul_f32_e32 v18, v18, v0
	v_mul_f32_e32 v0, v2, v0
	v_add3_u32 v49, s35, v49, v50
	v_cvt_pk_bf16_f32 v0, v0, s0
	ds_write_b16 v49, v0 offset:59456
	v_mul_f32_e32 v0, v19, v42
	v_cvt_pk_bf16_f32 v0, v0, s0
	ds_write_b16 v49, v0 offset:59520
	v_mul_f32_e32 v0, v3, v42
	v_cvt_pk_bf16_f32 v0, v0, s0
	ds_write_b16 v49, v0 offset:59584
	v_mul_f32_e32 v0, v20, v43
	v_cvt_pk_bf16_f32 v0, v0, s0
	ds_write_b16 v49, v0 offset:59648
	v_mul_f32_e32 v0, v4, v43
	v_cvt_pk_bf16_f32 v0, v0, s0
	ds_write_b16 v49, v0 offset:59712
	v_mul_f32_e32 v0, v21, v44
	v_cvt_pk_bf16_f32 v0, v0, s0
	ds_write_b16 v49, v0 offset:59776
	v_mul_f32_e32 v0, v5, v44
	v_cvt_pk_bf16_f32 v0, v0, s0
	ds_write_b16 v49, v0 offset:59840
	v_mul_f32_e32 v0, v22, v45
	v_cvt_pk_bf16_f32 v0, v0, s0
	ds_write_b16 v49, v0 offset:60416
	v_mul_f32_e32 v0, v6, v45
	v_cvt_pk_bf16_f32 v0, v0, s0
	ds_write_b16 v49, v0 offset:60480
	v_mul_f32_e32 v0, v23, v46
	v_cvt_pk_bf16_f32 v0, v0, s0
	ds_write_b16 v49, v0 offset:60544
	v_mul_f32_e32 v0, v7, v46
	v_cvt_pk_bf16_f32 v0, v0, s0
	ds_write_b16 v49, v0 offset:60608
	v_mul_f32_e32 v0, v24, v47
	v_cvt_pk_bf16_f32 v0, v0, s0
	ds_write_b16 v49, v0 offset:60672
	v_mul_f32_e32 v0, v8, v47
	v_cvt_pk_bf16_f32 v0, v0, s0
	s_waitcnt lgkmcnt(13)
	v_rcp_f32_e32 v34, v34
	ds_write_b16 v49, v0 offset:60736
	v_mul_f32_e32 v0, v25, v48
	v_cvt_pk_bf16_f32 v0, v0, s0
	ds_write_b16 v49, v0 offset:60800
	v_mul_f32_e32 v0, v9, v48
	v_cvt_pk_bf16_f32 v0, v0, s0
	v_rcp_f32_e32 v35, v35
	ds_write_b16 v49, v0 offset:60864
	v_mul_f32_e32 v0, v26, v34
	v_cvt_pk_bf16_f32 v0, v0, s0
	ds_write_b16 v49, v0 offset:61440
	v_mul_f32_e32 v0, v10, v34
	v_cvt_pk_bf16_f32 v0, v0, s0
	v_rcp_f32_e32 v36, v36
	ds_write_b16 v49, v0 offset:61504
	v_mul_f32_e32 v0, v27, v35
	v_cvt_pk_bf16_f32 v0, v0, s0
	ds_write_b16 v49, v0 offset:61568
	v_mul_f32_e32 v0, v11, v35
	v_cvt_pk_bf16_f32 v0, v0, s0
	v_rcp_f32_e32 v37, v37
	ds_write_b16 v49, v0 offset:61632
	v_mul_f32_e32 v0, v28, v36
	v_cvt_pk_bf16_f32 v0, v0, s0
	ds_write_b16 v49, v0 offset:61696
	v_mul_f32_e32 v0, v12, v36
	v_cvt_pk_bf16_f32 v0, v0, s0
	s_waitcnt lgkmcnt(14)
	v_rcp_f32_e32 v38, v38
	ds_write_b16 v49, v0 offset:61760
	v_mul_f32_e32 v0, v29, v37
	v_cvt_pk_bf16_f32 v0, v0, s0
	ds_write_b16 v49, v0 offset:61824
	v_mul_f32_e32 v0, v13, v37
	v_cvt_pk_bf16_f32 v0, v0, s0
	v_rcp_f32_e32 v39, v39
	ds_write_b16 v49, v0 offset:61888
	v_mul_f32_e32 v0, v30, v38
	v_cvt_pk_bf16_f32 v0, v0, s0
	ds_write_b16 v49, v0 offset:62464
	v_mul_f32_e32 v0, v14, v38
	v_cvt_pk_bf16_f32 v0, v0, s0
	v_rcp_f32_e32 v40, v40
	ds_write_b16 v49, v0 offset:62528
	v_mul_f32_e32 v0, v31, v39
	v_cvt_pk_bf16_f32 v0, v0, s0
	ds_write_b16 v49, v0 offset:62592
	v_mul_f32_e32 v0, v15, v39
	v_cvt_pk_bf16_f32 v0, v0, s0
	v_rcp_f32_e32 v41, v41
	ds_write_b16 v49, v0 offset:62656
	v_mul_f32_e32 v0, v32, v40
	v_cvt_pk_bf16_f32 v0, v0, s0
	ds_write_b16 v49, v0 offset:62720
	v_mul_f32_e32 v0, v16, v40
	v_cvt_pk_bf16_f32 v0, v0, s0
	ds_write_b16 v49, v0 offset:62784
	v_mul_f32_e32 v0, v33, v41
	v_cvt_pk_bf16_f32 v0, v0, s0
	ds_write_b16 v49, v0 offset:62848
	v_mul_f32_e32 v0, v17, v41
	v_cvt_pk_bf16_f32 v0, v0, s0
	ds_write_b16 v49, v0 offset:62912
	v_lshlrev_b32_e32 v0, 1, v200
	v_cvt_pk_bf16_f32 v18, v18, s0
	s_add_u32 s2, s30, s2
	v_and_b32_e32 v0, 0x70, v0
	ds_write_b16 v49, v18 offset:59392
	s_addc_u32 s3, s31, s3
	v_lshrrev_b32_e32 v14, 3, v199
	v_add_u32_e32 v15, s35, v0
	s_waitcnt lgkmcnt(0)
	v_lshl_add_u64 v[10:11], s[2:3], 0, v[0:1]
	v_lshl_add_u32 v0, v14, 7, v15
	v_or_b32_e32 v16, 8, v14
	ds_read_b128 v[2:5], v0 offset:59392
	v_lshl_add_u32 v6, v16, 7, v15
	ds_read_b128 v[6:9], v6 offset:59392
	v_lshlrev_b32_e32 v0, 11, v14
	v_lshl_add_u64 v[12:13], v[10:11], 0, v[0:1]
	v_lshlrev_b32_e32 v0, 11, v16
	s_waitcnt lgkmcnt(1)
	global_store_dwordx4 v[12:13], v[2:5], off
	s_nop 1
	v_lshl_add_u64 v[2:3], v[10:11], 0, v[0:1]
	v_or_b32_e32 v0, 16, v14
	s_waitcnt lgkmcnt(0)
	global_store_dwordx4 v[2:3], v[6:9], off
	v_lshl_add_u32 v2, v0, 7, v15
	v_or_b32_e32 v14, 24, v14
	ds_read_b128 v[2:5], v2 offset:59392
	v_lshl_add_u32 v6, v14, 7, v15
	ds_read_b128 v[6:9], v6 offset:59392
	v_lshlrev_b32_e32 v0, 11, v0
	v_lshl_add_u64 v[12:13], v[10:11], 0, v[0:1]
	v_lshlrev_b32_e32 v0, 11, v14
	s_waitcnt lgkmcnt(1)
	global_store_dwordx4 v[12:13], v[2:5], off
	s_nop 1
	v_lshl_add_u64 v[2:3], v[10:11], 0, v[0:1]
	s_waitcnt lgkmcnt(0)
	global_store_dwordx4 v[2:3], v[6:9], off
	s_setprio 0
	s_waitcnt lgkmcnt(0)
	s_barrier
	s_branch .LBB0_207
